# prompt cumsum sequences: coalesced loads/stores with XOR-swizzled LDS transposes instead of 2KB-strided per-lane blocks
# baseline (speedup 1.0000x reference)
.LBB0_362:
	s_and_b64 s[34:35], s[22:23], exec
	s_cselect_b32 s2, s20, s2
	s_ashr_i32 s38, s2, 3
	s_and_b32 s21, s2, 7
	s_and_b64 s[22:23], s[22:23], exec
	s_movk_i32 s2, 0x1000
	s_cselect_b32 s50, s2, 0x810
	s_add_i32 s2, s50, 63
	s_ashr_i32 s39, s38, 31
	v_readlane_b32 s52, v253, 0
	s_lshr_b32 s51, s2, 6
	s_lshl_b64 s[22:23], s[38:39], 9
	v_readlane_b32 s54, v253, 2
	v_readlane_b32 s53, v253, 1
	v_readlane_b32 s55, v253, 3
	v_readlane_b32 s56, v253, 4
	v_readlane_b32 s57, v253, 5
	v_readlane_b32 s58, v253, 6
	v_readlane_b32 s59, v253, 7
	s_add_u32 s22, s54, s22
	s_addc_u32 s23, s55, s23
	v_readlane_b32 s52, v253, 22
	s_lshl_b64 s[34:35], s[38:39], 16
	v_readlane_b32 s66, v253, 36
	v_readlane_b32 s67, v253, 37
	s_add_u32 s2, s66, s34
	s_addc_u32 s35, s67, s35
	s_lshl_b32 s40, s21, 2
	s_add_u32 s34, s2, s40
	s_addc_u32 s35, s35, 0
	s_lshl_b64 s[38:39], s[38:39], 17
	s_add_u32 s2, s47, s40
	s_addc_u32 s40, s48, 0
	v_mul_u32_u24_e32 v4, s51, v5
	s_add_u32 s38, s2, s38
	v_lshlrev_b32_e32 v2, 5, v4
	s_addc_u32 s39, s40, s39
	v_lshlrev_b32_e32 v17, 3, v4
	v_lshl_add_u64 v[6:7], s[38:39], 0, v[2:3]
	v_mov_b32_e32 v18, 0
	v_cndmask_b32_e64 v19, 0, 1, s[12:13]
	v_mov_b64_e32 v[8:9], v[6:7]
	v_mov_b32_e32 v2, v17
	v_mov_b32_e32 v20, v4
	s_mov_b32 s52, s51
	v_readlane_b32 s53, v253, 23
	v_readlane_b32 s54, v253, 24
	v_readlane_b32 s55, v253, 25
	v_readlane_b32 s56, v253, 26
	v_readlane_b32 s57, v253, 27
	v_readlane_b32 s58, v253, 28
	v_readlane_b32 s59, v253, 29
	v_readlane_b32 s60, v253, 30
	v_readlane_b32 s61, v253, 31
	v_readlane_b32 s62, v253, 32
	v_readlane_b32 s63, v253, 33
	v_readlane_b32 s64, v253, 34
	v_readlane_b32 s65, v253, 35
	s_cmp_gt_i32 s20, 31
	s_cbranch_scc1 .Lcs_sample
	v_readfirstlane_b32 s2, v227
	v_lshlrev_b32_e32 v22, 5, v5
	v_mov_b32_e32 v23, 0
	s_mov_b32 s40, 0x1000
	s_mov_b32 s41, 0
	s_lshr_b32 s2, s2, 6
	s_lshl_b32 s2, s2, 14
	v_lshl_add_u64 v[22:23], v[22:23], 0, s[38:39]
	global_load_dword v30, v[22:23], off
	global_load_dword v31, v[22:23], off offset:2048
	v_lshl_add_u64 v[22:23], v[22:23], 0, s[40:41]
	global_load_dword v32, v[22:23], off
	global_load_dword v33, v[22:23], off offset:2048
	v_lshl_add_u64 v[22:23], v[22:23], 0, s[40:41]
	global_load_dword v34, v[22:23], off
	global_load_dword v35, v[22:23], off offset:2048
	v_lshl_add_u64 v[22:23], v[22:23], 0, s[40:41]
	global_load_dword v36, v[22:23], off
	global_load_dword v37, v[22:23], off offset:2048
	v_lshl_add_u64 v[22:23], v[22:23], 0, s[40:41]
	global_load_dword v38, v[22:23], off
	global_load_dword v39, v[22:23], off offset:2048
	v_lshl_add_u64 v[22:23], v[22:23], 0, s[40:41]
	global_load_dword v40, v[22:23], off
	global_load_dword v41, v[22:23], off offset:2048
	v_lshl_add_u64 v[22:23], v[22:23], 0, s[40:41]
	global_load_dword v42, v[22:23], off
	global_load_dword v43, v[22:23], off offset:2048
	v_lshl_add_u64 v[22:23], v[22:23], 0, s[40:41]
	global_load_dword v44, v[22:23], off
	global_load_dword v45, v[22:23], off offset:2048
	v_lshl_add_u64 v[22:23], v[22:23], 0, s[40:41]
	global_load_dword v46, v[22:23], off
	global_load_dword v47, v[22:23], off offset:2048
	v_lshl_add_u64 v[22:23], v[22:23], 0, s[40:41]
	global_load_dword v48, v[22:23], off
	global_load_dword v49, v[22:23], off offset:2048
	v_lshl_add_u64 v[22:23], v[22:23], 0, s[40:41]
	global_load_dword v50, v[22:23], off
	global_load_dword v51, v[22:23], off offset:2048
	v_lshl_add_u64 v[22:23], v[22:23], 0, s[40:41]
	global_load_dword v52, v[22:23], off
	global_load_dword v53, v[22:23], off offset:2048
	v_lshl_add_u64 v[22:23], v[22:23], 0, s[40:41]
	global_load_dword v54, v[22:23], off
	global_load_dword v55, v[22:23], off offset:2048
	v_lshl_add_u64 v[22:23], v[22:23], 0, s[40:41]
	global_load_dword v56, v[22:23], off
	global_load_dword v57, v[22:23], off offset:2048
	v_lshl_add_u64 v[22:23], v[22:23], 0, s[40:41]
	global_load_dword v58, v[22:23], off
	global_load_dword v59, v[22:23], off offset:2048
	v_lshl_add_u64 v[22:23], v[22:23], 0, s[40:41]
	global_load_dword v60, v[22:23], off
	global_load_dword v61, v[22:23], off offset:2048
	v_lshl_add_u64 v[22:23], v[22:23], 0, s[40:41]
	global_load_dword v62, v[22:23], off
	global_load_dword v63, v[22:23], off offset:2048
	v_lshl_add_u64 v[22:23], v[22:23], 0, s[40:41]
	global_load_dword v64, v[22:23], off
	global_load_dword v65, v[22:23], off offset:2048
	v_lshl_add_u64 v[22:23], v[22:23], 0, s[40:41]
	global_load_dword v66, v[22:23], off
	global_load_dword v67, v[22:23], off offset:2048
	v_lshl_add_u64 v[22:23], v[22:23], 0, s[40:41]
	global_load_dword v68, v[22:23], off
	global_load_dword v69, v[22:23], off offset:2048
	v_lshl_add_u64 v[22:23], v[22:23], 0, s[40:41]
	global_load_dword v70, v[22:23], off
	global_load_dword v71, v[22:23], off offset:2048
	v_lshl_add_u64 v[22:23], v[22:23], 0, s[40:41]
	global_load_dword v72, v[22:23], off
	global_load_dword v73, v[22:23], off offset:2048
	v_lshl_add_u64 v[22:23], v[22:23], 0, s[40:41]
	global_load_dword v74, v[22:23], off
	global_load_dword v75, v[22:23], off offset:2048
	v_lshl_add_u64 v[22:23], v[22:23], 0, s[40:41]
	global_load_dword v76, v[22:23], off
	global_load_dword v77, v[22:23], off offset:2048
	v_lshl_add_u64 v[22:23], v[22:23], 0, s[40:41]
	global_load_dword v78, v[22:23], off
	global_load_dword v79, v[22:23], off offset:2048
	v_lshl_add_u64 v[22:23], v[22:23], 0, s[40:41]
	global_load_dword v80, v[22:23], off
	global_load_dword v81, v[22:23], off offset:2048
	v_lshl_add_u64 v[22:23], v[22:23], 0, s[40:41]
	global_load_dword v82, v[22:23], off
	global_load_dword v83, v[22:23], off offset:2048
	v_lshl_add_u64 v[22:23], v[22:23], 0, s[40:41]
	global_load_dword v84, v[22:23], off
	global_load_dword v85, v[22:23], off offset:2048
	v_lshl_add_u64 v[22:23], v[22:23], 0, s[40:41]
	global_load_dword v86, v[22:23], off
	global_load_dword v87, v[22:23], off offset:2048
	v_lshl_add_u64 v[22:23], v[22:23], 0, s[40:41]
	global_load_dword v88, v[22:23], off
	global_load_dword v89, v[22:23], off offset:2048
	v_lshl_add_u64 v[22:23], v[22:23], 0, s[40:41]
	global_load_dword v90, v[22:23], off
	global_load_dword v91, v[22:23], off offset:2048
	v_lshl_add_u64 v[22:23], v[22:23], 0, s[40:41]
	global_load_dword v92, v[22:23], off
	global_load_dword v93, v[22:23], off offset:2048
	v_lshl_add_u32 v25, v5, 8, s2
	s_waitcnt vmcnt(56)
	v_xor_b32_e32 v24, 0, v5
	v_lshl_add_u32 v24, v24, 2, s2
	ds_write_b32 v24, v30
	v_xor_b32_e32 v24, 1, v5
	v_lshl_add_u32 v24, v24, 2, s2
	ds_write_b32 v24, v31 offset:256
	v_xor_b32_e32 v24, 2, v5
	v_lshl_add_u32 v24, v24, 2, s2
	ds_write_b32 v24, v32 offset:512
	v_xor_b32_e32 v24, 3, v5
	v_lshl_add_u32 v24, v24, 2, s2
	ds_write_b32 v24, v33 offset:768
	v_xor_b32_e32 v24, 4, v5
	v_lshl_add_u32 v24, v24, 2, s2
	ds_write_b32 v24, v34 offset:1024
	v_xor_b32_e32 v24, 5, v5
	v_lshl_add_u32 v24, v24, 2, s2
	ds_write_b32 v24, v35 offset:1280
	v_xor_b32_e32 v24, 6, v5
	v_lshl_add_u32 v24, v24, 2, s2
	ds_write_b32 v24, v36 offset:1536
	v_xor_b32_e32 v24, 7, v5
	v_lshl_add_u32 v24, v24, 2, s2
	ds_write_b32 v24, v37 offset:1792
	s_waitcnt vmcnt(48)
	v_xor_b32_e32 v24, 8, v5
	v_lshl_add_u32 v24, v24, 2, s2
	ds_write_b32 v24, v38 offset:2048
	v_xor_b32_e32 v24, 9, v5
	v_lshl_add_u32 v24, v24, 2, s2
	ds_write_b32 v24, v39 offset:2304
	v_xor_b32_e32 v24, 10, v5
	v_lshl_add_u32 v24, v24, 2, s2
	ds_write_b32 v24, v40 offset:2560
	v_xor_b32_e32 v24, 11, v5
	v_lshl_add_u32 v24, v24, 2, s2
	ds_write_b32 v24, v41 offset:2816
	v_xor_b32_e32 v24, 12, v5
	v_lshl_add_u32 v24, v24, 2, s2
	ds_write_b32 v24, v42 offset:3072
	v_xor_b32_e32 v24, 13, v5
	v_lshl_add_u32 v24, v24, 2, s2
	ds_write_b32 v24, v43 offset:3328
	v_xor_b32_e32 v24, 14, v5
	v_lshl_add_u32 v24, v24, 2, s2
	ds_write_b32 v24, v44 offset:3584
	v_xor_b32_e32 v24, 15, v5
	v_lshl_add_u32 v24, v24, 2, s2
	ds_write_b32 v24, v45 offset:3840
	s_waitcnt vmcnt(40)
	v_xor_b32_e32 v24, 16, v5
	v_lshl_add_u32 v24, v24, 2, s2
	ds_write_b32 v24, v46 offset:4096
	v_xor_b32_e32 v24, 17, v5
	v_lshl_add_u32 v24, v24, 2, s2
	ds_write_b32 v24, v47 offset:4352
	v_xor_b32_e32 v24, 18, v5
	v_lshl_add_u32 v24, v24, 2, s2
	ds_write_b32 v24, v48 offset:4608
	v_xor_b32_e32 v24, 19, v5
	v_lshl_add_u32 v24, v24, 2, s2
	ds_write_b32 v24, v49 offset:4864
	v_xor_b32_e32 v24, 20, v5
	v_lshl_add_u32 v24, v24, 2, s2
	ds_write_b32 v24, v50 offset:5120
	v_xor_b32_e32 v24, 21, v5
	v_lshl_add_u32 v24, v24, 2, s2
	ds_write_b32 v24, v51 offset:5376
	v_xor_b32_e32 v24, 22, v5
	v_lshl_add_u32 v24, v24, 2, s2
	ds_write_b32 v24, v52 offset:5632
	v_xor_b32_e32 v24, 23, v5
	v_lshl_add_u32 v24, v24, 2, s2
	ds_write_b32 v24, v53 offset:5888
	s_waitcnt vmcnt(32)
	v_xor_b32_e32 v24, 24, v5
	v_lshl_add_u32 v24, v24, 2, s2
	ds_write_b32 v24, v54 offset:6144
	v_xor_b32_e32 v24, 25, v5
	v_lshl_add_u32 v24, v24, 2, s2
	ds_write_b32 v24, v55 offset:6400
	v_xor_b32_e32 v24, 26, v5
	v_lshl_add_u32 v24, v24, 2, s2
	ds_write_b32 v24, v56 offset:6656
	v_xor_b32_e32 v24, 27, v5
	v_lshl_add_u32 v24, v24, 2, s2
	ds_write_b32 v24, v57 offset:6912
	v_xor_b32_e32 v24, 28, v5
	v_lshl_add_u32 v24, v24, 2, s2
	ds_write_b32 v24, v58 offset:7168
	v_xor_b32_e32 v24, 29, v5
	v_lshl_add_u32 v24, v24, 2, s2
	ds_write_b32 v24, v59 offset:7424
	v_xor_b32_e32 v24, 30, v5
	v_lshl_add_u32 v24, v24, 2, s2
	ds_write_b32 v24, v60 offset:7680
	v_xor_b32_e32 v24, 31, v5
	v_lshl_add_u32 v24, v24, 2, s2
	ds_write_b32 v24, v61 offset:7936
	s_waitcnt vmcnt(24)
	v_xor_b32_e32 v24, 32, v5
	v_lshl_add_u32 v24, v24, 2, s2
	ds_write_b32 v24, v62 offset:8192
	v_xor_b32_e32 v24, 33, v5
	v_lshl_add_u32 v24, v24, 2, s2
	ds_write_b32 v24, v63 offset:8448
	v_xor_b32_e32 v24, 34, v5
	v_lshl_add_u32 v24, v24, 2, s2
	ds_write_b32 v24, v64 offset:8704
	v_xor_b32_e32 v24, 35, v5
	v_lshl_add_u32 v24, v24, 2, s2
	ds_write_b32 v24, v65 offset:8960
	v_xor_b32_e32 v24, 36, v5
	v_lshl_add_u32 v24, v24, 2, s2
	ds_write_b32 v24, v66 offset:9216
	v_xor_b32_e32 v24, 37, v5
	v_lshl_add_u32 v24, v24, 2, s2
	ds_write_b32 v24, v67 offset:9472
	v_xor_b32_e32 v24, 38, v5
	v_lshl_add_u32 v24, v24, 2, s2
	ds_write_b32 v24, v68 offset:9728
	v_xor_b32_e32 v24, 39, v5
	v_lshl_add_u32 v24, v24, 2, s2
	ds_write_b32 v24, v69 offset:9984
	s_waitcnt vmcnt(16)
	v_xor_b32_e32 v24, 40, v5
	v_lshl_add_u32 v24, v24, 2, s2
	ds_write_b32 v24, v70 offset:10240
	v_xor_b32_e32 v24, 41, v5
	v_lshl_add_u32 v24, v24, 2, s2
	ds_write_b32 v24, v71 offset:10496
	v_xor_b32_e32 v24, 42, v5
	v_lshl_add_u32 v24, v24, 2, s2
	ds_write_b32 v24, v72 offset:10752
	v_xor_b32_e32 v24, 43, v5
	v_lshl_add_u32 v24, v24, 2, s2
	ds_write_b32 v24, v73 offset:11008
	v_xor_b32_e32 v24, 44, v5
	v_lshl_add_u32 v24, v24, 2, s2
	ds_write_b32 v24, v74 offset:11264
	v_xor_b32_e32 v24, 45, v5
	v_lshl_add_u32 v24, v24, 2, s2
	ds_write_b32 v24, v75 offset:11520
	v_xor_b32_e32 v24, 46, v5
	v_lshl_add_u32 v24, v24, 2, s2
	ds_write_b32 v24, v76 offset:11776
	v_xor_b32_e32 v24, 47, v5
	v_lshl_add_u32 v24, v24, 2, s2
	ds_write_b32 v24, v77 offset:12032
	s_waitcnt vmcnt(8)
	v_xor_b32_e32 v24, 48, v5
	v_lshl_add_u32 v24, v24, 2, s2
	ds_write_b32 v24, v78 offset:12288
	v_xor_b32_e32 v24, 49, v5
	v_lshl_add_u32 v24, v24, 2, s2
	ds_write_b32 v24, v79 offset:12544
	v_xor_b32_e32 v24, 50, v5
	v_lshl_add_u32 v24, v24, 2, s2
	ds_write_b32 v24, v80 offset:12800
	v_xor_b32_e32 v24, 51, v5
	v_lshl_add_u32 v24, v24, 2, s2
	ds_write_b32 v24, v81 offset:13056
	v_xor_b32_e32 v24, 52, v5
	v_lshl_add_u32 v24, v24, 2, s2
	ds_write_b32 v24, v82 offset:13312
	v_xor_b32_e32 v24, 53, v5
	v_lshl_add_u32 v24, v24, 2, s2
	ds_write_b32 v24, v83 offset:13568
	v_xor_b32_e32 v24, 54, v5
	v_lshl_add_u32 v24, v24, 2, s2
	ds_write_b32 v24, v84 offset:13824
	v_xor_b32_e32 v24, 55, v5
	v_lshl_add_u32 v24, v24, 2, s2
	ds_write_b32 v24, v85 offset:14080
	s_waitcnt vmcnt(0)
	v_xor_b32_e32 v24, 56, v5
	v_lshl_add_u32 v24, v24, 2, s2
	ds_write_b32 v24, v86 offset:14336
	v_xor_b32_e32 v24, 57, v5
	v_lshl_add_u32 v24, v24, 2, s2
	ds_write_b32 v24, v87 offset:14592
	v_xor_b32_e32 v24, 58, v5
	v_lshl_add_u32 v24, v24, 2, s2
	ds_write_b32 v24, v88 offset:14848
	v_xor_b32_e32 v24, 59, v5
	v_lshl_add_u32 v24, v24, 2, s2
	ds_write_b32 v24, v89 offset:15104
	v_xor_b32_e32 v24, 60, v5
	v_lshl_add_u32 v24, v24, 2, s2
	ds_write_b32 v24, v90 offset:15360
	v_xor_b32_e32 v24, 61, v5
	v_lshl_add_u32 v24, v24, 2, s2
	ds_write_b32 v24, v91 offset:15616
	v_xor_b32_e32 v24, 62, v5
	v_lshl_add_u32 v24, v24, 2, s2
	ds_write_b32 v24, v92 offset:15872
	v_xor_b32_e32 v24, 63, v5
	v_lshl_add_u32 v24, v24, 2, s2
	ds_write_b32 v24, v93 offset:16128
	s_waitcnt lgkmcnt(0)
	v_xor_b32_e32 v24, 0, v5
	v_lshl_add_u32 v24, v24, 2, v25
	ds_read_b32 v30, v24
	v_xor_b32_e32 v24, 1, v5
	v_lshl_add_u32 v24, v24, 2, v25
	ds_read_b32 v31, v24
	v_xor_b32_e32 v24, 2, v5
	v_lshl_add_u32 v24, v24, 2, v25
	ds_read_b32 v32, v24
	v_xor_b32_e32 v24, 3, v5
	v_lshl_add_u32 v24, v24, 2, v25
	ds_read_b32 v33, v24
	v_xor_b32_e32 v24, 4, v5
	v_lshl_add_u32 v24, v24, 2, v25
	ds_read_b32 v34, v24
	v_xor_b32_e32 v24, 5, v5
	v_lshl_add_u32 v24, v24, 2, v25
	ds_read_b32 v35, v24
	v_xor_b32_e32 v24, 6, v5
	v_lshl_add_u32 v24, v24, 2, v25
	ds_read_b32 v36, v24
	v_xor_b32_e32 v24, 7, v5
	v_lshl_add_u32 v24, v24, 2, v25
	ds_read_b32 v37, v24
	v_xor_b32_e32 v24, 8, v5
	v_lshl_add_u32 v24, v24, 2, v25
	ds_read_b32 v38, v24
	v_xor_b32_e32 v24, 9, v5
	v_lshl_add_u32 v24, v24, 2, v25
	ds_read_b32 v39, v24
	v_xor_b32_e32 v24, 10, v5
	v_lshl_add_u32 v24, v24, 2, v25
	ds_read_b32 v40, v24
	v_xor_b32_e32 v24, 11, v5
	v_lshl_add_u32 v24, v24, 2, v25
	ds_read_b32 v41, v24
	v_xor_b32_e32 v24, 12, v5
	v_lshl_add_u32 v24, v24, 2, v25
	ds_read_b32 v42, v24
	v_xor_b32_e32 v24, 13, v5
	v_lshl_add_u32 v24, v24, 2, v25
	ds_read_b32 v43, v24
	v_xor_b32_e32 v24, 14, v5
	v_lshl_add_u32 v24, v24, 2, v25
	ds_read_b32 v44, v24
	v_xor_b32_e32 v24, 15, v5
	v_lshl_add_u32 v24, v24, 2, v25
	ds_read_b32 v45, v24
	v_xor_b32_e32 v24, 16, v5
	v_lshl_add_u32 v24, v24, 2, v25
	ds_read_b32 v46, v24
	v_xor_b32_e32 v24, 17, v5
	v_lshl_add_u32 v24, v24, 2, v25
	ds_read_b32 v47, v24
	v_xor_b32_e32 v24, 18, v5
	v_lshl_add_u32 v24, v24, 2, v25
	ds_read_b32 v48, v24
	v_xor_b32_e32 v24, 19, v5
	v_lshl_add_u32 v24, v24, 2, v25
	ds_read_b32 v49, v24
	v_xor_b32_e32 v24, 20, v5
	v_lshl_add_u32 v24, v24, 2, v25
	ds_read_b32 v50, v24
	v_xor_b32_e32 v24, 21, v5
	v_lshl_add_u32 v24, v24, 2, v25
	ds_read_b32 v51, v24
	v_xor_b32_e32 v24, 22, v5
	v_lshl_add_u32 v24, v24, 2, v25
	ds_read_b32 v52, v24
	v_xor_b32_e32 v24, 23, v5
	v_lshl_add_u32 v24, v24, 2, v25
	ds_read_b32 v53, v24
	v_xor_b32_e32 v24, 24, v5
	v_lshl_add_u32 v24, v24, 2, v25
	ds_read_b32 v54, v24
	v_xor_b32_e32 v24, 25, v5
	v_lshl_add_u32 v24, v24, 2, v25
	ds_read_b32 v55, v24
	v_xor_b32_e32 v24, 26, v5
	v_lshl_add_u32 v24, v24, 2, v25
	ds_read_b32 v56, v24
	v_xor_b32_e32 v24, 27, v5
	v_lshl_add_u32 v24, v24, 2, v25
	ds_read_b32 v57, v24
	v_xor_b32_e32 v24, 28, v5
	v_lshl_add_u32 v24, v24, 2, v25
	ds_read_b32 v58, v24
	v_xor_b32_e32 v24, 29, v5
	v_lshl_add_u32 v24, v24, 2, v25
	ds_read_b32 v59, v24
	v_xor_b32_e32 v24, 30, v5
	v_lshl_add_u32 v24, v24, 2, v25
	ds_read_b32 v60, v24
	v_xor_b32_e32 v24, 31, v5
	v_lshl_add_u32 v24, v24, 2, v25
	ds_read_b32 v61, v24
	v_xor_b32_e32 v24, 32, v5
	v_lshl_add_u32 v24, v24, 2, v25
	ds_read_b32 v62, v24
	v_xor_b32_e32 v24, 33, v5
	v_lshl_add_u32 v24, v24, 2, v25
	ds_read_b32 v63, v24
	v_xor_b32_e32 v24, 34, v5
	v_lshl_add_u32 v24, v24, 2, v25
	ds_read_b32 v64, v24
	v_xor_b32_e32 v24, 35, v5
	v_lshl_add_u32 v24, v24, 2, v25
	ds_read_b32 v65, v24
	v_xor_b32_e32 v24, 36, v5
	v_lshl_add_u32 v24, v24, 2, v25
	ds_read_b32 v66, v24
	v_xor_b32_e32 v24, 37, v5
	v_lshl_add_u32 v24, v24, 2, v25
	ds_read_b32 v67, v24
	v_xor_b32_e32 v24, 38, v5
	v_lshl_add_u32 v24, v24, 2, v25
	ds_read_b32 v68, v24
	v_xor_b32_e32 v24, 39, v5
	v_lshl_add_u32 v24, v24, 2, v25
	ds_read_b32 v69, v24
	v_xor_b32_e32 v24, 40, v5
	v_lshl_add_u32 v24, v24, 2, v25
	ds_read_b32 v70, v24
	v_xor_b32_e32 v24, 41, v5
	v_lshl_add_u32 v24, v24, 2, v25
	ds_read_b32 v71, v24
	v_xor_b32_e32 v24, 42, v5
	v_lshl_add_u32 v24, v24, 2, v25
	ds_read_b32 v72, v24
	v_xor_b32_e32 v24, 43, v5
	v_lshl_add_u32 v24, v24, 2, v25
	ds_read_b32 v73, v24
	v_xor_b32_e32 v24, 44, v5
	v_lshl_add_u32 v24, v24, 2, v25
	ds_read_b32 v74, v24
	v_xor_b32_e32 v24, 45, v5
	v_lshl_add_u32 v24, v24, 2, v25
	ds_read_b32 v75, v24
	v_xor_b32_e32 v24, 46, v5
	v_lshl_add_u32 v24, v24, 2, v25
	ds_read_b32 v76, v24
	v_xor_b32_e32 v24, 47, v5
	v_lshl_add_u32 v24, v24, 2, v25
	ds_read_b32 v77, v24
	v_xor_b32_e32 v24, 48, v5
	v_lshl_add_u32 v24, v24, 2, v25
	ds_read_b32 v78, v24
	v_xor_b32_e32 v24, 49, v5
	v_lshl_add_u32 v24, v24, 2, v25
	ds_read_b32 v79, v24
	v_xor_b32_e32 v24, 50, v5
	v_lshl_add_u32 v24, v24, 2, v25
	ds_read_b32 v80, v24
	v_xor_b32_e32 v24, 51, v5
	v_lshl_add_u32 v24, v24, 2, v25
	ds_read_b32 v81, v24
	v_xor_b32_e32 v24, 52, v5
	v_lshl_add_u32 v24, v24, 2, v25
	ds_read_b32 v82, v24
	v_xor_b32_e32 v24, 53, v5
	v_lshl_add_u32 v24, v24, 2, v25
	ds_read_b32 v83, v24
	v_xor_b32_e32 v24, 54, v5
	v_lshl_add_u32 v24, v24, 2, v25
	ds_read_b32 v84, v24
	v_xor_b32_e32 v24, 55, v5
	v_lshl_add_u32 v24, v24, 2, v25
	ds_read_b32 v85, v24
	v_xor_b32_e32 v24, 56, v5
	v_lshl_add_u32 v24, v24, 2, v25
	ds_read_b32 v86, v24
	v_xor_b32_e32 v24, 57, v5
	v_lshl_add_u32 v24, v24, 2, v25
	ds_read_b32 v87, v24
	v_xor_b32_e32 v24, 58, v5
	v_lshl_add_u32 v24, v24, 2, v25
	ds_read_b32 v88, v24
	v_xor_b32_e32 v24, 59, v5
	v_lshl_add_u32 v24, v24, 2, v25
	ds_read_b32 v89, v24
	v_xor_b32_e32 v24, 60, v5
	v_lshl_add_u32 v24, v24, 2, v25
	ds_read_b32 v90, v24
	v_xor_b32_e32 v24, 61, v5
	v_lshl_add_u32 v24, v24, 2, v25
	ds_read_b32 v91, v24
	v_xor_b32_e32 v24, 62, v5
	v_lshl_add_u32 v24, v24, 2, v25
	ds_read_b32 v92, v24
	v_xor_b32_e32 v24, 63, v5
	v_lshl_add_u32 v24, v24, 2, v25
	ds_read_b32 v93, v24
	s_waitcnt lgkmcnt(0)
	v_add_f32_e32 v18, v18, v30
	v_add_f32_e32 v18, v18, v31
	v_add_f32_e32 v18, v18, v32
	v_add_f32_e32 v18, v18, v33
	v_add_f32_e32 v18, v18, v34
	v_add_f32_e32 v18, v18, v35
	v_add_f32_e32 v18, v18, v36
	v_add_f32_e32 v18, v18, v37
	v_add_f32_e32 v18, v18, v38
	v_add_f32_e32 v18, v18, v39
	v_add_f32_e32 v18, v18, v40
	v_add_f32_e32 v18, v18, v41
	v_add_f32_e32 v18, v18, v42
	v_add_f32_e32 v18, v18, v43
	v_add_f32_e32 v18, v18, v44
	v_add_f32_e32 v18, v18, v45
	v_add_f32_e32 v18, v18, v46
	v_add_f32_e32 v18, v18, v47
	v_add_f32_e32 v18, v18, v48
	v_add_f32_e32 v18, v18, v49
	v_add_f32_e32 v18, v18, v50
	v_add_f32_e32 v18, v18, v51
	v_add_f32_e32 v18, v18, v52
	v_add_f32_e32 v18, v18, v53
	v_add_f32_e32 v18, v18, v54
	v_add_f32_e32 v18, v18, v55
	v_add_f32_e32 v18, v18, v56
	v_add_f32_e32 v18, v18, v57
	v_add_f32_e32 v18, v18, v58
	v_add_f32_e32 v18, v18, v59
	v_add_f32_e32 v18, v18, v60
	v_add_f32_e32 v18, v18, v61
	v_add_f32_e32 v18, v18, v62
	v_add_f32_e32 v18, v18, v63
	v_add_f32_e32 v18, v18, v64
	v_add_f32_e32 v18, v18, v65
	v_add_f32_e32 v18, v18, v66
	v_add_f32_e32 v18, v18, v67
	v_add_f32_e32 v18, v18, v68
	v_add_f32_e32 v18, v18, v69
	v_add_f32_e32 v18, v18, v70
	v_add_f32_e32 v18, v18, v71
	v_add_f32_e32 v18, v18, v72
	v_add_f32_e32 v18, v18, v73
	v_add_f32_e32 v18, v18, v74
	v_add_f32_e32 v18, v18, v75
	v_add_f32_e32 v18, v18, v76
	v_add_f32_e32 v18, v18, v77
	v_add_f32_e32 v18, v18, v78
	v_add_f32_e32 v18, v18, v79
	v_add_f32_e32 v18, v18, v80
	v_add_f32_e32 v18, v18, v81
	v_add_f32_e32 v18, v18, v82
	v_add_f32_e32 v18, v18, v83
	v_add_f32_e32 v18, v18, v84
	v_add_f32_e32 v18, v18, v85
	v_add_f32_e32 v18, v18, v86
	v_add_f32_e32 v18, v18, v87
	v_add_f32_e32 v18, v18, v88
	v_add_f32_e32 v18, v18, v89
	v_add_f32_e32 v18, v18, v90
	v_add_f32_e32 v18, v18, v91
	v_add_f32_e32 v18, v18, v92
	v_add_f32_e32 v18, v18, v93
	s_branch .Lcs_scan

.Lcs_scan:
	ds_bpermute_b32 v2, v1, v18
	s_waitcnt lgkmcnt(0)
	v_add_f32_e32 v2, v18, v2
	v_cndmask_b32_e64 v2, v2, v18, s[0:1]
	ds_bpermute_b32 v8, v12, v2
	s_waitcnt lgkmcnt(0)
	v_add_f32_e32 v8, v2, v8
	v_cndmask_b32_e64 v2, v8, v2, s[14:15]
	ds_bpermute_b32 v8, v13, v2
	s_waitcnt lgkmcnt(0)
	v_add_f32_e32 v8, v2, v8
	v_cndmask_b32_e64 v2, v8, v2, s[4:5]
	ds_bpermute_b32 v8, v14, v2
	s_waitcnt lgkmcnt(0)
	v_add_f32_e32 v8, v2, v8
	v_cndmask_b32_e64 v2, v8, v2, s[6:7]
	ds_bpermute_b32 v8, v15, v2
	s_waitcnt lgkmcnt(0)
	v_add_f32_e32 v8, v2, v8
	v_cndmask_b32_e64 v10, v8, v2, s[8:9]
	ds_bpermute_b32 v11, v16, v10
	v_lshlrev_b32_e32 v2, 2, v4
	v_lshl_add_u64 v[8:9], s[36:37], 0, v[2:3]
	s_waitcnt lgkmcnt(0)
	v_add_f32_e32 v2, v10, v11
	v_cndmask_b32_e64 v2, v2, v10, s[10:11]
	v_sub_f32_e32 v18, v2, v18
	s_cmp_gt_i32 s20, 31
	s_cbranch_scc1 .Lcs_sample2
	v_add_f32_e32 v18, v18, v30
	v_mul_f32_e32 v30, 0x3fb8aa3b, v18
	v_add_f32_e32 v18, v18, v31
	v_mul_f32_e32 v31, 0x3fb8aa3b, v18
	v_add_f32_e32 v18, v18, v32
	v_mul_f32_e32 v32, 0x3fb8aa3b, v18
	v_add_f32_e32 v18, v18, v33
	v_mul_f32_e32 v33, 0x3fb8aa3b, v18
	v_add_f32_e32 v18, v18, v34
	v_mul_f32_e32 v34, 0x3fb8aa3b, v18
	v_add_f32_e32 v18, v18, v35
	v_mul_f32_e32 v35, 0x3fb8aa3b, v18
	v_add_f32_e32 v18, v18, v36
	v_mul_f32_e32 v36, 0x3fb8aa3b, v18
	v_add_f32_e32 v18, v18, v37
	v_mul_f32_e32 v37, 0x3fb8aa3b, v18
	v_add_f32_e32 v18, v18, v38
	v_mul_f32_e32 v38, 0x3fb8aa3b, v18
	v_add_f32_e32 v18, v18, v39
	v_mul_f32_e32 v39, 0x3fb8aa3b, v18
	v_add_f32_e32 v18, v18, v40
	v_mul_f32_e32 v40, 0x3fb8aa3b, v18
	v_add_f32_e32 v18, v18, v41
	v_mul_f32_e32 v41, 0x3fb8aa3b, v18
	v_add_f32_e32 v18, v18, v42
	v_mul_f32_e32 v42, 0x3fb8aa3b, v18
	v_add_f32_e32 v18, v18, v43
	v_mul_f32_e32 v43, 0x3fb8aa3b, v18
	v_add_f32_e32 v18, v18, v44
	v_mul_f32_e32 v44, 0x3fb8aa3b, v18
	v_add_f32_e32 v18, v18, v45
	v_mul_f32_e32 v45, 0x3fb8aa3b, v18
	v_add_f32_e32 v18, v18, v46
	v_mul_f32_e32 v46, 0x3fb8aa3b, v18
	v_add_f32_e32 v18, v18, v47
	v_mul_f32_e32 v47, 0x3fb8aa3b, v18
	v_add_f32_e32 v18, v18, v48
	v_mul_f32_e32 v48, 0x3fb8aa3b, v18
	v_add_f32_e32 v18, v18, v49
	v_mul_f32_e32 v49, 0x3fb8aa3b, v18
	v_add_f32_e32 v18, v18, v50
	v_mul_f32_e32 v50, 0x3fb8aa3b, v18
	v_add_f32_e32 v18, v18, v51
	v_mul_f32_e32 v51, 0x3fb8aa3b, v18
	v_add_f32_e32 v18, v18, v52
	v_mul_f32_e32 v52, 0x3fb8aa3b, v18
	v_add_f32_e32 v18, v18, v53
	v_mul_f32_e32 v53, 0x3fb8aa3b, v18
	v_add_f32_e32 v18, v18, v54
	v_mul_f32_e32 v54, 0x3fb8aa3b, v18
	v_add_f32_e32 v18, v18, v55
	v_mul_f32_e32 v55, 0x3fb8aa3b, v18
	v_add_f32_e32 v18, v18, v56
	v_mul_f32_e32 v56, 0x3fb8aa3b, v18
	v_add_f32_e32 v18, v18, v57
	v_mul_f32_e32 v57, 0x3fb8aa3b, v18
	v_add_f32_e32 v18, v18, v58
	v_mul_f32_e32 v58, 0x3fb8aa3b, v18
	v_add_f32_e32 v18, v18, v59
	v_mul_f32_e32 v59, 0x3fb8aa3b, v18
	v_add_f32_e32 v18, v18, v60
	v_mul_f32_e32 v60, 0x3fb8aa3b, v18
	v_add_f32_e32 v18, v18, v61
	v_mul_f32_e32 v61, 0x3fb8aa3b, v18
	v_add_f32_e32 v18, v18, v62
	v_mul_f32_e32 v62, 0x3fb8aa3b, v18
	v_add_f32_e32 v18, v18, v63
	v_mul_f32_e32 v63, 0x3fb8aa3b, v18
	v_add_f32_e32 v18, v18, v64
	v_mul_f32_e32 v64, 0x3fb8aa3b, v18
	v_add_f32_e32 v18, v18, v65
	v_mul_f32_e32 v65, 0x3fb8aa3b, v18
	v_add_f32_e32 v18, v18, v66
	v_mul_f32_e32 v66, 0x3fb8aa3b, v18
	v_add_f32_e32 v18, v18, v67
	v_mul_f32_e32 v67, 0x3fb8aa3b, v18
	v_add_f32_e32 v18, v18, v68
	v_mul_f32_e32 v68, 0x3fb8aa3b, v18
	v_add_f32_e32 v18, v18, v69
	v_mul_f32_e32 v69, 0x3fb8aa3b, v18
	v_add_f32_e32 v18, v18, v70
	v_mul_f32_e32 v70, 0x3fb8aa3b, v18
	v_add_f32_e32 v18, v18, v71
	v_mul_f32_e32 v71, 0x3fb8aa3b, v18
	v_add_f32_e32 v18, v18, v72
	v_mul_f32_e32 v72, 0x3fb8aa3b, v18
	v_add_f32_e32 v18, v18, v73
	v_mul_f32_e32 v73, 0x3fb8aa3b, v18
	v_add_f32_e32 v18, v18, v74
	v_mul_f32_e32 v74, 0x3fb8aa3b, v18
	v_add_f32_e32 v18, v18, v75
	v_mul_f32_e32 v75, 0x3fb8aa3b, v18
	v_add_f32_e32 v18, v18, v76
	v_mul_f32_e32 v76, 0x3fb8aa3b, v18
	v_add_f32_e32 v18, v18, v77
	v_mul_f32_e32 v77, 0x3fb8aa3b, v18
	v_add_f32_e32 v18, v18, v78
	v_mul_f32_e32 v78, 0x3fb8aa3b, v18
	v_add_f32_e32 v18, v18, v79
	v_mul_f32_e32 v79, 0x3fb8aa3b, v18
	v_add_f32_e32 v18, v18, v80
	v_mul_f32_e32 v80, 0x3fb8aa3b, v18
	v_add_f32_e32 v18, v18, v81
	v_mul_f32_e32 v81, 0x3fb8aa3b, v18
	v_add_f32_e32 v18, v18, v82
	v_mul_f32_e32 v82, 0x3fb8aa3b, v18
	v_add_f32_e32 v18, v18, v83
	v_mul_f32_e32 v83, 0x3fb8aa3b, v18
	v_add_f32_e32 v18, v18, v84
	v_mul_f32_e32 v84, 0x3fb8aa3b, v18
	v_add_f32_e32 v18, v18, v85
	v_mul_f32_e32 v85, 0x3fb8aa3b, v18
	v_add_f32_e32 v18, v18, v86
	v_mul_f32_e32 v86, 0x3fb8aa3b, v18
	v_add_f32_e32 v18, v18, v87
	v_mul_f32_e32 v87, 0x3fb8aa3b, v18
	v_add_f32_e32 v18, v18, v88
	v_mul_f32_e32 v88, 0x3fb8aa3b, v18
	v_add_f32_e32 v18, v18, v89
	v_mul_f32_e32 v89, 0x3fb8aa3b, v18
	v_add_f32_e32 v18, v18, v90
	v_mul_f32_e32 v90, 0x3fb8aa3b, v18
	v_add_f32_e32 v18, v18, v91
	v_mul_f32_e32 v91, 0x3fb8aa3b, v18
	v_add_f32_e32 v18, v18, v92
	v_mul_f32_e32 v92, 0x3fb8aa3b, v18
	v_add_f32_e32 v18, v18, v93
	v_mul_f32_e32 v93, 0x3fb8aa3b, v18
	v_xor_b32_e32 v24, 0, v5
	v_lshl_add_u32 v24, v24, 2, v25
	ds_write_b32 v24, v30
	v_xor_b32_e32 v24, 1, v5
	v_lshl_add_u32 v24, v24, 2, v25
	ds_write_b32 v24, v31
	v_xor_b32_e32 v24, 2, v5
	v_lshl_add_u32 v24, v24, 2, v25
	ds_write_b32 v24, v32
	v_xor_b32_e32 v24, 3, v5
	v_lshl_add_u32 v24, v24, 2, v25
	ds_write_b32 v24, v33
	v_xor_b32_e32 v24, 4, v5
	v_lshl_add_u32 v24, v24, 2, v25
	ds_write_b32 v24, v34
	v_xor_b32_e32 v24, 5, v5
	v_lshl_add_u32 v24, v24, 2, v25
	ds_write_b32 v24, v35
	v_xor_b32_e32 v24, 6, v5
	v_lshl_add_u32 v24, v24, 2, v25
	ds_write_b32 v24, v36
	v_xor_b32_e32 v24, 7, v5
	v_lshl_add_u32 v24, v24, 2, v25
	ds_write_b32 v24, v37
	v_xor_b32_e32 v24, 8, v5
	v_lshl_add_u32 v24, v24, 2, v25
	ds_write_b32 v24, v38
	v_xor_b32_e32 v24, 9, v5
	v_lshl_add_u32 v24, v24, 2, v25
	ds_write_b32 v24, v39
	v_xor_b32_e32 v24, 10, v5
	v_lshl_add_u32 v24, v24, 2, v25
	ds_write_b32 v24, v40
	v_xor_b32_e32 v24, 11, v5
	v_lshl_add_u32 v24, v24, 2, v25
	ds_write_b32 v24, v41
	v_xor_b32_e32 v24, 12, v5
	v_lshl_add_u32 v24, v24, 2, v25
	ds_write_b32 v24, v42
	v_xor_b32_e32 v24, 13, v5
	v_lshl_add_u32 v24, v24, 2, v25
	ds_write_b32 v24, v43
	v_xor_b32_e32 v24, 14, v5
	v_lshl_add_u32 v24, v24, 2, v25
	ds_write_b32 v24, v44
	v_xor_b32_e32 v24, 15, v5
	v_lshl_add_u32 v24, v24, 2, v25
	ds_write_b32 v24, v45
	v_xor_b32_e32 v24, 16, v5
	v_lshl_add_u32 v24, v24, 2, v25
	ds_write_b32 v24, v46
	v_xor_b32_e32 v24, 17, v5
	v_lshl_add_u32 v24, v24, 2, v25
	ds_write_b32 v24, v47
	v_xor_b32_e32 v24, 18, v5
	v_lshl_add_u32 v24, v24, 2, v25
	ds_write_b32 v24, v48
	v_xor_b32_e32 v24, 19, v5
	v_lshl_add_u32 v24, v24, 2, v25
	ds_write_b32 v24, v49
	v_xor_b32_e32 v24, 20, v5
	v_lshl_add_u32 v24, v24, 2, v25
	ds_write_b32 v24, v50
	v_xor_b32_e32 v24, 21, v5
	v_lshl_add_u32 v24, v24, 2, v25
	ds_write_b32 v24, v51
	v_xor_b32_e32 v24, 22, v5
	v_lshl_add_u32 v24, v24, 2, v25
	ds_write_b32 v24, v52
	v_xor_b32_e32 v24, 23, v5
	v_lshl_add_u32 v24, v24, 2, v25
	ds_write_b32 v24, v53
	v_xor_b32_e32 v24, 24, v5
	v_lshl_add_u32 v24, v24, 2, v25
	ds_write_b32 v24, v54
	v_xor_b32_e32 v24, 25, v5
	v_lshl_add_u32 v24, v24, 2, v25
	ds_write_b32 v24, v55
	v_xor_b32_e32 v24, 26, v5
	v_lshl_add_u32 v24, v24, 2, v25
	ds_write_b32 v24, v56
	v_xor_b32_e32 v24, 27, v5
	v_lshl_add_u32 v24, v24, 2, v25
	ds_write_b32 v24, v57
	v_xor_b32_e32 v24, 28, v5
	v_lshl_add_u32 v24, v24, 2, v25
	ds_write_b32 v24, v58
	v_xor_b32_e32 v24, 29, v5
	v_lshl_add_u32 v24, v24, 2, v25
	ds_write_b32 v24, v59
	v_xor_b32_e32 v24, 30, v5
	v_lshl_add_u32 v24, v24, 2, v25
	ds_write_b32 v24, v60
	v_xor_b32_e32 v24, 31, v5
	v_lshl_add_u32 v24, v24, 2, v25
	ds_write_b32 v24, v61
	v_xor_b32_e32 v24, 32, v5
	v_lshl_add_u32 v24, v24, 2, v25
	ds_write_b32 v24, v62
	v_xor_b32_e32 v24, 33, v5
	v_lshl_add_u32 v24, v24, 2, v25
	ds_write_b32 v24, v63
	v_xor_b32_e32 v24, 34, v5
	v_lshl_add_u32 v24, v24, 2, v25
	ds_write_b32 v24, v64
	v_xor_b32_e32 v24, 35, v5
	v_lshl_add_u32 v24, v24, 2, v25
	ds_write_b32 v24, v65
	v_xor_b32_e32 v24, 36, v5
	v_lshl_add_u32 v24, v24, 2, v25
	ds_write_b32 v24, v66
	v_xor_b32_e32 v24, 37, v5
	v_lshl_add_u32 v24, v24, 2, v25
	ds_write_b32 v24, v67
	v_xor_b32_e32 v24, 38, v5
	v_lshl_add_u32 v24, v24, 2, v25
	ds_write_b32 v24, v68
	v_xor_b32_e32 v24, 39, v5
	v_lshl_add_u32 v24, v24, 2, v25
	ds_write_b32 v24, v69
	v_xor_b32_e32 v24, 40, v5
	v_lshl_add_u32 v24, v24, 2, v25
	ds_write_b32 v24, v70
	v_xor_b32_e32 v24, 41, v5
	v_lshl_add_u32 v24, v24, 2, v25
	ds_write_b32 v24, v71
	v_xor_b32_e32 v24, 42, v5
	v_lshl_add_u32 v24, v24, 2, v25
	ds_write_b32 v24, v72
	v_xor_b32_e32 v24, 43, v5
	v_lshl_add_u32 v24, v24, 2, v25
	ds_write_b32 v24, v73
	v_xor_b32_e32 v24, 44, v5
	v_lshl_add_u32 v24, v24, 2, v25
	ds_write_b32 v24, v74
	v_xor_b32_e32 v24, 45, v5
	v_lshl_add_u32 v24, v24, 2, v25
	ds_write_b32 v24, v75
	v_xor_b32_e32 v24, 46, v5
	v_lshl_add_u32 v24, v24, 2, v25
	ds_write_b32 v24, v76
	v_xor_b32_e32 v24, 47, v5
	v_lshl_add_u32 v24, v24, 2, v25
	ds_write_b32 v24, v77
	v_xor_b32_e32 v24, 48, v5
	v_lshl_add_u32 v24, v24, 2, v25
	ds_write_b32 v24, v78
	v_xor_b32_e32 v24, 49, v5
	v_lshl_add_u32 v24, v24, 2, v25
	ds_write_b32 v24, v79
	v_xor_b32_e32 v24, 50, v5
	v_lshl_add_u32 v24, v24, 2, v25
	ds_write_b32 v24, v80
	v_xor_b32_e32 v24, 51, v5
	v_lshl_add_u32 v24, v24, 2, v25
	ds_write_b32 v24, v81
	v_xor_b32_e32 v24, 52, v5
	v_lshl_add_u32 v24, v24, 2, v25
	ds_write_b32 v24, v82
	v_xor_b32_e32 v24, 53, v5
	v_lshl_add_u32 v24, v24, 2, v25
	ds_write_b32 v24, v83
	v_xor_b32_e32 v24, 54, v5
	v_lshl_add_u32 v24, v24, 2, v25
	ds_write_b32 v24, v84
	v_xor_b32_e32 v24, 55, v5
	v_lshl_add_u32 v24, v24, 2, v25
	ds_write_b32 v24, v85
	v_xor_b32_e32 v24, 56, v5
	v_lshl_add_u32 v24, v24, 2, v25
	ds_write_b32 v24, v86
	v_xor_b32_e32 v24, 57, v5
	v_lshl_add_u32 v24, v24, 2, v25
	ds_write_b32 v24, v87
	v_xor_b32_e32 v24, 58, v5
	v_lshl_add_u32 v24, v24, 2, v25
	ds_write_b32 v24, v88
	v_xor_b32_e32 v24, 59, v5
	v_lshl_add_u32 v24, v24, 2, v25
	ds_write_b32 v24, v89
	v_xor_b32_e32 v24, 60, v5
	v_lshl_add_u32 v24, v24, 2, v25
	ds_write_b32 v24, v90
	v_xor_b32_e32 v24, 61, v5
	v_lshl_add_u32 v24, v24, 2, v25
	ds_write_b32 v24, v91
	v_xor_b32_e32 v24, 62, v5
	v_lshl_add_u32 v24, v24, 2, v25
	ds_write_b32 v24, v92
	v_xor_b32_e32 v24, 63, v5
	v_lshl_add_u32 v24, v24, 2, v25
	ds_write_b32 v24, v93
	v_lshlrev_b32_e32 v22, 2, v5
	v_mov_b32_e32 v23, 0
	v_lshl_add_u64 v[22:23], v[22:23], 0, s[36:37]
	s_waitcnt lgkmcnt(0)
	v_xor_b32_e32 v24, 0, v5
	v_lshl_add_u32 v24, v24, 2, s2
	ds_read_b32 v30, v24
	v_xor_b32_e32 v24, 1, v5
	v_lshl_add_u32 v24, v24, 2, s2
	ds_read_b32 v31, v24 offset:256
	v_xor_b32_e32 v24, 2, v5
	v_lshl_add_u32 v24, v24, 2, s2
	ds_read_b32 v32, v24 offset:512
	v_xor_b32_e32 v24, 3, v5
	v_lshl_add_u32 v24, v24, 2, s2
	ds_read_b32 v33, v24 offset:768
	v_xor_b32_e32 v24, 4, v5
	v_lshl_add_u32 v24, v24, 2, s2
	ds_read_b32 v34, v24 offset:1024
	v_xor_b32_e32 v24, 5, v5
	v_lshl_add_u32 v24, v24, 2, s2
	ds_read_b32 v35, v24 offset:1280
	v_xor_b32_e32 v24, 6, v5
	v_lshl_add_u32 v24, v24, 2, s2
	ds_read_b32 v36, v24 offset:1536
	v_xor_b32_e32 v24, 7, v5
	v_lshl_add_u32 v24, v24, 2, s2
	ds_read_b32 v37, v24 offset:1792
	v_xor_b32_e32 v24, 8, v5
	v_lshl_add_u32 v24, v24, 2, s2
	ds_read_b32 v38, v24 offset:2048
	v_xor_b32_e32 v24, 9, v5
	v_lshl_add_u32 v24, v24, 2, s2
	ds_read_b32 v39, v24 offset:2304
	v_xor_b32_e32 v24, 10, v5
	v_lshl_add_u32 v24, v24, 2, s2
	ds_read_b32 v40, v24 offset:2560
	v_xor_b32_e32 v24, 11, v5
	v_lshl_add_u32 v24, v24, 2, s2
	ds_read_b32 v41, v24 offset:2816
	v_xor_b32_e32 v24, 12, v5
	v_lshl_add_u32 v24, v24, 2, s2
	ds_read_b32 v42, v24 offset:3072
	v_xor_b32_e32 v24, 13, v5
	v_lshl_add_u32 v24, v24, 2, s2
	ds_read_b32 v43, v24 offset:3328
	v_xor_b32_e32 v24, 14, v5
	v_lshl_add_u32 v24, v24, 2, s2
	ds_read_b32 v44, v24 offset:3584
	v_xor_b32_e32 v24, 15, v5
	v_lshl_add_u32 v24, v24, 2, s2
	ds_read_b32 v45, v24 offset:3840
	v_xor_b32_e32 v24, 16, v5
	v_lshl_add_u32 v24, v24, 2, s2
	ds_read_b32 v46, v24 offset:4096
	v_xor_b32_e32 v24, 17, v5
	v_lshl_add_u32 v24, v24, 2, s2
	ds_read_b32 v47, v24 offset:4352
	v_xor_b32_e32 v24, 18, v5
	v_lshl_add_u32 v24, v24, 2, s2
	ds_read_b32 v48, v24 offset:4608
	v_xor_b32_e32 v24, 19, v5
	v_lshl_add_u32 v24, v24, 2, s2
	ds_read_b32 v49, v24 offset:4864
	v_xor_b32_e32 v24, 20, v5
	v_lshl_add_u32 v24, v24, 2, s2
	ds_read_b32 v50, v24 offset:5120
	v_xor_b32_e32 v24, 21, v5
	v_lshl_add_u32 v24, v24, 2, s2
	ds_read_b32 v51, v24 offset:5376
	v_xor_b32_e32 v24, 22, v5
	v_lshl_add_u32 v24, v24, 2, s2
	ds_read_b32 v52, v24 offset:5632
	v_xor_b32_e32 v24, 23, v5
	v_lshl_add_u32 v24, v24, 2, s2
	ds_read_b32 v53, v24 offset:5888
	v_xor_b32_e32 v24, 24, v5
	v_lshl_add_u32 v24, v24, 2, s2
	ds_read_b32 v54, v24 offset:6144
	v_xor_b32_e32 v24, 25, v5
	v_lshl_add_u32 v24, v24, 2, s2
	ds_read_b32 v55, v24 offset:6400
	v_xor_b32_e32 v24, 26, v5
	v_lshl_add_u32 v24, v24, 2, s2
	ds_read_b32 v56, v24 offset:6656
	v_xor_b32_e32 v24, 27, v5
	v_lshl_add_u32 v24, v24, 2, s2
	ds_read_b32 v57, v24 offset:6912
	v_xor_b32_e32 v24, 28, v5
	v_lshl_add_u32 v24, v24, 2, s2
	ds_read_b32 v58, v24 offset:7168
	v_xor_b32_e32 v24, 29, v5
	v_lshl_add_u32 v24, v24, 2, s2
	ds_read_b32 v59, v24 offset:7424
	v_xor_b32_e32 v24, 30, v5
	v_lshl_add_u32 v24, v24, 2, s2
	ds_read_b32 v60, v24 offset:7680
	v_xor_b32_e32 v24, 31, v5
	v_lshl_add_u32 v24, v24, 2, s2
	ds_read_b32 v61, v24 offset:7936
	v_xor_b32_e32 v24, 32, v5
	v_lshl_add_u32 v24, v24, 2, s2
	ds_read_b32 v62, v24 offset:8192
	v_xor_b32_e32 v24, 33, v5
	v_lshl_add_u32 v24, v24, 2, s2
	ds_read_b32 v63, v24 offset:8448
	v_xor_b32_e32 v24, 34, v5
	v_lshl_add_u32 v24, v24, 2, s2
	ds_read_b32 v64, v24 offset:8704
	v_xor_b32_e32 v24, 35, v5
	v_lshl_add_u32 v24, v24, 2, s2
	ds_read_b32 v65, v24 offset:8960
	v_xor_b32_e32 v24, 36, v5
	v_lshl_add_u32 v24, v24, 2, s2
	ds_read_b32 v66, v24 offset:9216
	v_xor_b32_e32 v24, 37, v5
	v_lshl_add_u32 v24, v24, 2, s2
	ds_read_b32 v67, v24 offset:9472
	v_xor_b32_e32 v24, 38, v5
	v_lshl_add_u32 v24, v24, 2, s2
	ds_read_b32 v68, v24 offset:9728
	v_xor_b32_e32 v24, 39, v5
	v_lshl_add_u32 v24, v24, 2, s2
	ds_read_b32 v69, v24 offset:9984
	v_xor_b32_e32 v24, 40, v5
	v_lshl_add_u32 v24, v24, 2, s2
	ds_read_b32 v70, v24 offset:10240
	v_xor_b32_e32 v24, 41, v5
	v_lshl_add_u32 v24, v24, 2, s2
	ds_read_b32 v71, v24 offset:10496
	v_xor_b32_e32 v24, 42, v5
	v_lshl_add_u32 v24, v24, 2, s2
	ds_read_b32 v72, v24 offset:10752
	v_xor_b32_e32 v24, 43, v5
	v_lshl_add_u32 v24, v24, 2, s2
	ds_read_b32 v73, v24 offset:11008
	v_xor_b32_e32 v24, 44, v5
	v_lshl_add_u32 v24, v24, 2, s2
	ds_read_b32 v74, v24 offset:11264
	v_xor_b32_e32 v24, 45, v5
	v_lshl_add_u32 v24, v24, 2, s2
	ds_read_b32 v75, v24 offset:11520
	v_xor_b32_e32 v24, 46, v5
	v_lshl_add_u32 v24, v24, 2, s2
	ds_read_b32 v76, v24 offset:11776
	v_xor_b32_e32 v24, 47, v5
	v_lshl_add_u32 v24, v24, 2, s2
	ds_read_b32 v77, v24 offset:12032
	v_xor_b32_e32 v24, 48, v5
	v_lshl_add_u32 v24, v24, 2, s2
	ds_read_b32 v78, v24 offset:12288
	v_xor_b32_e32 v24, 49, v5
	v_lshl_add_u32 v24, v24, 2, s2
	ds_read_b32 v79, v24 offset:12544
	v_xor_b32_e32 v24, 50, v5
	v_lshl_add_u32 v24, v24, 2, s2
	ds_read_b32 v80, v24 offset:12800
	v_xor_b32_e32 v24, 51, v5
	v_lshl_add_u32 v24, v24, 2, s2
	ds_read_b32 v81, v24 offset:13056
	v_xor_b32_e32 v24, 52, v5
	v_lshl_add_u32 v24, v24, 2, s2
	ds_read_b32 v82, v24 offset:13312
	v_xor_b32_e32 v24, 53, v5
	v_lshl_add_u32 v24, v24, 2, s2
	ds_read_b32 v83, v24 offset:13568
	v_xor_b32_e32 v24, 54, v5
	v_lshl_add_u32 v24, v24, 2, s2
	ds_read_b32 v84, v24 offset:13824
	v_xor_b32_e32 v24, 55, v5
	v_lshl_add_u32 v24, v24, 2, s2
	ds_read_b32 v85, v24 offset:14080
	v_xor_b32_e32 v24, 56, v5
	v_lshl_add_u32 v24, v24, 2, s2
	ds_read_b32 v86, v24 offset:14336
	v_xor_b32_e32 v24, 57, v5
	v_lshl_add_u32 v24, v24, 2, s2
	ds_read_b32 v87, v24 offset:14592
	v_xor_b32_e32 v24, 58, v5
	v_lshl_add_u32 v24, v24, 2, s2
	ds_read_b32 v88, v24 offset:14848
	v_xor_b32_e32 v24, 59, v5
	v_lshl_add_u32 v24, v24, 2, s2
	ds_read_b32 v89, v24 offset:15104
	v_xor_b32_e32 v24, 60, v5
	v_lshl_add_u32 v24, v24, 2, s2
	ds_read_b32 v90, v24 offset:15360
	v_xor_b32_e32 v24, 61, v5
	v_lshl_add_u32 v24, v24, 2, s2
	ds_read_b32 v91, v24 offset:15616
	v_xor_b32_e32 v24, 62, v5
	v_lshl_add_u32 v24, v24, 2, s2
	ds_read_b32 v92, v24 offset:15872
	v_xor_b32_e32 v24, 63, v5
	v_lshl_add_u32 v24, v24, 2, s2
	ds_read_b32 v93, v24 offset:16128
	s_waitcnt lgkmcnt(0)
	global_store_dword v[22:23], v30, off
	global_store_dword v[22:23], v31, off offset:256
	global_store_dword v[22:23], v32, off offset:512
	global_store_dword v[22:23], v33, off offset:768
	global_store_dword v[22:23], v34, off offset:1024
	global_store_dword v[22:23], v35, off offset:1280
	global_store_dword v[22:23], v36, off offset:1536
	global_store_dword v[22:23], v37, off offset:1792
	global_store_dword v[22:23], v38, off offset:2048
	global_store_dword v[22:23], v39, off offset:2304
	global_store_dword v[22:23], v40, off offset:2560
	global_store_dword v[22:23], v41, off offset:2816
	global_store_dword v[22:23], v42, off offset:3072
	global_store_dword v[22:23], v43, off offset:3328
	global_store_dword v[22:23], v44, off offset:3584
	global_store_dword v[22:23], v45, off offset:3840
	v_lshl_add_u64 v[22:23], v[22:23], 0, s[40:41]
	global_store_dword v[22:23], v46, off
	global_store_dword v[22:23], v47, off offset:256
	global_store_dword v[22:23], v48, off offset:512
	global_store_dword v[22:23], v49, off offset:768
	global_store_dword v[22:23], v50, off offset:1024
	global_store_dword v[22:23], v51, off offset:1280
	global_store_dword v[22:23], v52, off offset:1536
	global_store_dword v[22:23], v53, off offset:1792
	global_store_dword v[22:23], v54, off offset:2048
	global_store_dword v[22:23], v55, off offset:2304
	global_store_dword v[22:23], v56, off offset:2560
	global_store_dword v[22:23], v57, off offset:2816
	global_store_dword v[22:23], v58, off offset:3072
	global_store_dword v[22:23], v59, off offset:3328
	global_store_dword v[22:23], v60, off offset:3584
	global_store_dword v[22:23], v61, off offset:3840
	v_lshl_add_u64 v[22:23], v[22:23], 0, s[40:41]
	global_store_dword v[22:23], v62, off
	global_store_dword v[22:23], v63, off offset:256
	global_store_dword v[22:23], v64, off offset:512
	global_store_dword v[22:23], v65, off offset:768
	global_store_dword v[22:23], v66, off offset:1024
	global_store_dword v[22:23], v67, off offset:1280
	global_store_dword v[22:23], v68, off offset:1536
	global_store_dword v[22:23], v69, off offset:1792
	global_store_dword v[22:23], v70, off offset:2048
	global_store_dword v[22:23], v71, off offset:2304
	global_store_dword v[22:23], v72, off offset:2560
	global_store_dword v[22:23], v73, off offset:2816
	global_store_dword v[22:23], v74, off offset:3072
	global_store_dword v[22:23], v75, off offset:3328
	global_store_dword v[22:23], v76, off offset:3584
	global_store_dword v[22:23], v77, off offset:3840
	v_lshl_add_u64 v[22:23], v[22:23], 0, s[40:41]
	global_store_dword v[22:23], v78, off
	global_store_dword v[22:23], v79, off offset:256
	global_store_dword v[22:23], v80, off offset:512
	global_store_dword v[22:23], v81, off offset:768
	global_store_dword v[22:23], v82, off offset:1024
	global_store_dword v[22:23], v83, off offset:1280
	global_store_dword v[22:23], v84, off offset:1536
	global_store_dword v[22:23], v85, off offset:1792
	global_store_dword v[22:23], v86, off offset:2048
	global_store_dword v[22:23], v87, off offset:2304
	global_store_dword v[22:23], v88, off offset:2560
	global_store_dword v[22:23], v89, off offset:2816
	global_store_dword v[22:23], v90, off offset:3072
	global_store_dword v[22:23], v91, off offset:3328
	global_store_dword v[22:23], v92, off offset:3584
	global_store_dword v[22:23], v93, off offset:3840
	s_barrier
	s_branch .LBB0_357
